# v098 + static priority (7.4): generic GEMM K-loop drops its 16 per-segment s_setprio flips per iteration; waves 4-7 (wr==1 half) run the K-loop at priority 1, reset at loop exit
# speedup vs baseline: 1.0066x; 1.0066x over previous
; #define PG8_STAGE(bufoff, gbase, voff) do { _Pragma("unroll") for (int _i = 0; _i < 2; ++_i) \
;         __builtin_amdgcn_global_load_lds((const unsigned*)((const char*)(gbase) + (voff)[_i]), (PG8_LAS unsigned*)(lds + (bufoff) + ldsw + _i * 8192), 16, 0, 0); } while (0)
; #define PG8_LDA(dst, b, h) do { _Pragma("unroll") for (int m = 0; m < 4; ++m) _Pragma("unroll") for (int k = 0; k < 2; ++k) dst[m][k] = *(const PG8_LAS bf16x8*)(lds + PG8_SA(b, h) + aoff + m * 2048 + k * 1024); } while (0)
; #define PG8_LDB(dst, b, h) do { _Pragma("unroll") for (int n = 0; n < 2; ++n) _Pragma("unroll") for (int k = 0; k < 2; ++k) dst[n][k] = *(const PG8_LAS bf16x8*)(lds + PG8_SB(b, h) + boff + n * 2048 + k * 1024); } while (0)
; template <class Epi, class Sched, bool ALIGN_EPI = false>
; __device__ __forceinline__ void gemm_phase(PG8_LAS unsigned char* lds, const Gemm g, const Sched& S, const Epi& E, int tid_in) {
;     ...
;         for (int t = 0; t < nt; t += 2) {
;             const bool last = (t == nt - 2);
;             const char* a1 = cA + (size_t)(t + 1) * kstep;
;             const char* a2 = last ? nA : cA + (size_t)(t + 2) * kstep; const char* b2 = last ? nB : cB + (size_t)(t + 2) * kstep;
;             const char* a3 = a2 + kstep; const char* b3 = b2 + kstep;
;             if (last && has_next) S.a_ready(nxt);
;             E.mid(acc, cur, t, tid_, wr, wc);
;             PG8_LDB(B0, 0, 0); PG8_LDB(B1, 0, 1); PG8_SCHED; PG8_LDA(At, 0, 0); PG8_STAGE(PG8_SA(1, 1), a1 + hstepA, voffA);
;             PG8_WAIT_V(8); PG8_WAIT_L(0); PG8_BAR; PG8_MMA(0, 0, At, B0); PG8_MMA(0, 1, At, B1); PG8_BAR; PG8_SCHED;
;             PG8_LDA(At, 0, 1); PG8_STAGE(PG8_SB(0, 0), b2, voffB); PG8_STAGE(PG8_SB(0, 1), b2 + hstepB, voffB); PG8_STAGE(PG8_SA(0, 0), a2, voffA);
;             PG8_WAIT_V(8); PG8_WAIT_L(0); PG8_BAR; PG8_MMA(1, 0, At, B0); PG8_MMA(1, 1, At, B1); PG8_BAR; PG8_SCHED;
;             PG8_LDB(B0, 1, 0); PG8_LDB(B1, 1, 1); PG8_SCHED; PG8_LDA(At, 1, 0); PG8_STAGE(PG8_SA(0, 1), a2 + hstepA, voffA);
;             PG8_WAIT_V(8); PG8_WAIT_L(0); PG8_BAR; PG8_MMA(0, 0, At, B0); PG8_MMA(0, 1, At, B1); PG8_BAR; PG8_SCHED;
;             PG8_LDA(At, 1, 1); PG8_STAGE(PG8_SB(1, 0), b3, voffB); PG8_STAGE(PG8_SB(1, 1), b3 + hstepB, voffB); PG8_STAGE(PG8_SA(1, 0), a3, voffA);
;             PG8_WAIT_V(8); PG8_WAIT_L(0); PG8_BAR; PG8_MMA(1, 0, At, B0); PG8_MMA(1, 1, At, B1); PG8_BAR; PG8_SCHED;
.LBB0_266:
	s_and_b64 vcc, exec, s[12:13]
	s_cbranch_vccz .Lprio_skip
	s_setprio 1
.Lprio_skip:
	s_add_u32 s60, s60, 0x80
	s_addc_u32 s61, s61, 0
	s_add_u32 s57, s58, 0x100
	s_addc_u32 s62, s59, 0
	s_mov_b32 s58, 0
	s_cmp_eq_u32 s64, 2
	s_cbranch_scc1 .Lk_nopeel
	s_add_i32 s63, s58, 2
	s_add_u32 s22, s60, 0x80
	s_addc_u32 s23, s61, 0
	s_add_i32 s89, 0, 0x10000
	s_cmp_eq_u32 s77, s58
	s_cselect_b32 s59, s19, s23
	s_cselect_b32 s58, s18, s22
	v_add_u32_e32 v80, s89, v245
	s_cselect_b32 s23, s35, s62
	s_cselect_b32 s22, s34, s57
	s_add_i32 s90, 0, 0x14000
	ds_read_b128 v[130:133], v80
	ds_read_b128 v[134:137], v80 offset:1024
	ds_read_b128 v[138:141], v80 offset:2048
	ds_read_b128 v[142:145], v80 offset:3072
	v_add_u32_e32 v80, s90, v245
	ds_read_b128 v[146:149], v80
	ds_read_b128 v[150:153], v80 offset:1024
	ds_read_b128 v[154:157], v80 offset:2048
	ds_read_b128 v[158:161], v80 offset:3072
	s_mov_b32 m0, s74
	ds_read_b128 v[162:165], v248
	ds_read_b128 v[166:169], v248 offset:1024
	ds_read_b128 v[170:173], v248 offset:2048
	ds_read_b128 v[174:177], v248 offset:3072
	ds_read_b128 v[178:181], v248 offset:4096
	ds_read_b128 v[198:201], v248 offset:5120
	ds_read_b128 v[202:205], v248 offset:6144
	ds_read_b128 v[206:209], v248 offset:7168
	global_load_lds_dwordx4 v184, s[60:61]
	s_mov_b32 m0, s75
	s_nop 0
	global_load_lds_dwordx4 v188, s[60:61]
	s_add_i32 m0, s70, 0xc000
	s_nop 0
	global_load_lds_dwordx4 v194, s[60:61]
	s_add_i32 m0, s70, 0xe000
	s_nop 0
	global_load_lds_dwordx4 v196, s[60:61]
	s_waitcnt vmcnt(8)
	s_waitcnt lgkmcnt(0)
	v_mfma_f32_16x16x32_bf16 v[4:7], v[130:133], v[162:165], 0
	v_mfma_f32_16x16x32_bf16 v[0:3], v[138:141], v[162:165], 0
	s_barrier
	s_waitcnt lgkmcnt(0)
	v_mfma_f32_16x16x32_bf16 v[20:23], v[130:133], v[170:173], 0
	v_mfma_f32_16x16x32_bf16 v[16:19], v[138:141], v[170:173], 0
	v_mfma_f32_16x16x32_bf16 v[36:39], v[130:133], v[178:181], 0
	v_mfma_f32_16x16x32_bf16 v[32:35], v[138:141], v[178:181], 0
	v_mfma_f32_16x16x32_bf16 v[52:55], v[130:133], v[202:205], 0
	v_mfma_f32_16x16x32_bf16 v[48:51], v[138:141], v[202:205], 0
	v_mfma_f32_16x16x32_bf16 v[4:7], v[134:137], v[166:169], v[4:7]
	v_mfma_f32_16x16x32_bf16 v[0:3], v[142:145], v[166:169], v[0:3]
	v_mfma_f32_16x16x32_bf16 v[20:23], v[134:137], v[174:177], v[20:23]
	v_mfma_f32_16x16x32_bf16 v[16:19], v[142:145], v[174:177], v[16:19]
	v_mfma_f32_16x16x32_bf16 v[36:39], v[134:137], v[198:201], v[36:39]
	v_mfma_f32_16x16x32_bf16 v[32:35], v[142:145], v[198:201], v[32:35]
	v_mfma_f32_16x16x32_bf16 v[52:55], v[134:137], v[206:209], v[52:55]
	v_mfma_f32_16x16x32_bf16 v[48:51], v[142:145], v[206:209], v[48:51]
	v_mfma_f32_16x16x32_bf16 v[12:15], v[146:149], v[162:165], 0
	v_mfma_f32_16x16x32_bf16 v[8:11], v[154:157], v[162:165], 0
	v_mfma_f32_16x16x32_bf16 v[28:31], v[146:149], v[170:173], 0
	v_mfma_f32_16x16x32_bf16 v[24:27], v[154:157], v[170:173], 0
	v_mfma_f32_16x16x32_bf16 v[44:47], v[146:149], v[178:181], 0
	v_mfma_f32_16x16x32_bf16 v[40:43], v[154:157], v[178:181], 0
	v_mfma_f32_16x16x32_bf16 v[60:63], v[146:149], v[202:205], 0
	v_mfma_f32_16x16x32_bf16 v[56:59], v[154:157], v[202:205], 0
	v_mfma_f32_16x16x32_bf16 v[12:15], v[150:153], v[166:169], v[12:15]
	v_mfma_f32_16x16x32_bf16 v[8:11], v[158:161], v[166:169], v[8:11]
	v_mfma_f32_16x16x32_bf16 v[28:31], v[150:153], v[174:177], v[28:31]
	v_mfma_f32_16x16x32_bf16 v[24:27], v[158:161], v[174:177], v[24:27]
	v_mfma_f32_16x16x32_bf16 v[44:47], v[150:153], v[198:201], v[44:47]
	v_mfma_f32_16x16x32_bf16 v[40:43], v[158:161], v[198:201], v[40:43]
	v_mfma_f32_16x16x32_bf16 v[60:63], v[150:153], v[206:209], v[60:63]
	v_mfma_f32_16x16x32_bf16 v[56:59], v[158:161], v[206:209], v[56:59]
	s_barrier
	s_add_i32 s89, s89, s69
	s_mov_b64 vcc, s[22:23]
	s_mov_b32 m0, s89
	ds_read_b128 v[162:165], v248 offset:16384
	ds_read_b128 v[166:169], v248 offset:17408
	ds_read_b128 v[170:173], v248 offset:18432
	ds_read_b128 v[174:177], v248 offset:19456
	ds_read_b128 v[178:181], v248 offset:20480
	ds_read_b128 v[198:201], v248 offset:21504
	ds_read_b128 v[202:205], v248 offset:22528
	ds_read_b128 v[206:209], v248 offset:23552
	global_load_lds_dwordx4 v186, s[22:23]
	s_add_i32 m0, s89, 0x2000
	s_add_u32 s22, s22, s33
	s_addc_u32 s23, s23, 0
	s_add_i32 s89, s90, s69
	global_load_lds_dwordx4 v190, vcc
	s_mov_b32 m0, s89
	s_nop 0
	global_load_lds_dwordx4 v186, s[22:23]
	s_add_i32 m0, s89, 0x2000
	s_nop 0
	global_load_lds_dwordx4 v190, s[22:23]
	s_waitcnt vmcnt(6)
	s_waitcnt lgkmcnt(0)
	v_mfma_f32_16x16x32_bf16 v[64:67], v[130:133], v[162:165], 0
	v_mfma_f32_16x16x32_bf16 v[68:71], v[138:141], v[162:165], 0
	s_barrier
	s_waitcnt lgkmcnt(0)
	v_mfma_f32_16x16x32_bf16 v[82:85], v[130:133], v[170:173], 0
	v_mfma_f32_16x16x32_bf16 v[86:89], v[138:141], v[170:173], 0
	v_mfma_f32_16x16x32_bf16 v[98:101], v[130:133], v[178:181], 0
	v_mfma_f32_16x16x32_bf16 v[102:105], v[138:141], v[178:181], 0
	v_mfma_f32_16x16x32_bf16 v[114:117], v[130:133], v[202:205], 0
	v_mfma_f32_16x16x32_bf16 v[118:121], v[138:141], v[202:205], 0
	v_mfma_f32_16x16x32_bf16 v[64:67], v[134:137], v[166:169], v[64:67]
	v_mfma_f32_16x16x32_bf16 v[68:71], v[142:145], v[166:169], v[68:71]
	v_mfma_f32_16x16x32_bf16 v[82:85], v[134:137], v[174:177], v[82:85]
	v_mfma_f32_16x16x32_bf16 v[86:89], v[142:145], v[174:177], v[86:89]
	v_mfma_f32_16x16x32_bf16 v[98:101], v[134:137], v[198:201], v[98:101]
	v_mfma_f32_16x16x32_bf16 v[102:105], v[142:145], v[198:201], v[102:105]
	v_mfma_f32_16x16x32_bf16 v[114:117], v[134:137], v[206:209], v[114:117]
	v_mfma_f32_16x16x32_bf16 v[118:121], v[142:145], v[206:209], v[118:121]
	v_mfma_f32_16x16x32_bf16 v[76:79], v[146:149], v[162:165], 0
	v_mfma_f32_16x16x32_bf16 v[72:75], v[154:157], v[162:165], 0
	v_mfma_f32_16x16x32_bf16 v[94:97], v[146:149], v[170:173], 0
	v_mfma_f32_16x16x32_bf16 v[90:93], v[154:157], v[170:173], 0
	v_mfma_f32_16x16x32_bf16 v[110:113], v[146:149], v[178:181], 0
	v_mfma_f32_16x16x32_bf16 v[106:109], v[154:157], v[178:181], 0
	v_mfma_f32_16x16x32_bf16 v[126:129], v[146:149], v[202:205], 0
	v_mfma_f32_16x16x32_bf16 v[122:125], v[154:157], v[202:205], 0
	v_mfma_f32_16x16x32_bf16 v[76:79], v[150:153], v[166:169], v[76:79]
	v_mfma_f32_16x16x32_bf16 v[72:75], v[158:161], v[166:169], v[72:75]
	v_mfma_f32_16x16x32_bf16 v[94:97], v[150:153], v[174:177], v[94:97]
	v_mfma_f32_16x16x32_bf16 v[90:93], v[158:161], v[174:177], v[90:93]
	v_mfma_f32_16x16x32_bf16 v[110:113], v[150:153], v[198:201], v[110:113]
	v_mfma_f32_16x16x32_bf16 v[106:109], v[158:161], v[198:201], v[106:109]
	v_mfma_f32_16x16x32_bf16 v[126:129], v[150:153], v[206:209], v[126:129]
	v_mfma_f32_16x16x32_bf16 v[122:125], v[158:161], v[206:209], v[122:125]
	s_barrier
; #define PG8_STAGE(bufoff, gbase, voff) do { _Pragma("unroll") for (int _i = 0; _i < 2; ++_i) \
;         __builtin_amdgcn_global_load_lds((const unsigned*)((const char*)(gbase) + (voff)[_i]), (PG8_LAS unsigned*)(lds + (bufoff) + ldsw + _i * 8192), 16, 0, 0); } while (0)
; #define PG8_LDA(dst, b, h) do { _Pragma("unroll") for (int m = 0; m < 4; ++m) _Pragma("unroll") for (int k = 0; k < 2; ++k) dst[m][k] = *(const PG8_LAS bf16x8*)(lds + PG8_SA(b, h) + aoff + m * 2048 + k * 1024); } while (0)
; #define PG8_LDB(dst, b, h) do { _Pragma("unroll") for (int n = 0; n < 2; ++n) _Pragma("unroll") for (int k = 0; k < 2; ++k) dst[n][k] = *(const PG8_LAS bf16x8*)(lds + PG8_SB(b, h) + boff + n * 2048 + k * 1024); } while (0)
; template <class Epi, class Sched, bool ALIGN_EPI = false>
; __device__ __forceinline__ void gemm_phase(PG8_LAS unsigned char* lds, const Gemm g, const Sched& S, const Epi& E, int tid_in) {
;     ...
;         for (int t = 0; t < nt; t += 2) {
;             const bool last = (t == nt - 2);
;             const char* a1 = cA + (size_t)(t + 1) * kstep;
;             const char* a2 = last ? nA : cA + (size_t)(t + 2) * kstep; const char* b2 = last ? nB : cB + (size_t)(t + 2) * kstep;
;             const char* a3 = a2 + kstep; const char* b3 = b2 + kstep;
;             if (last && has_next) S.a_ready(nxt);
;             E.mid(acc, cur, t, tid_, wr, wc);
;             PG8_LDB(B0, 0, 0); PG8_LDB(B1, 0, 1); PG8_SCHED; PG8_LDA(At, 0, 0); PG8_STAGE(PG8_SA(1, 1), a1 + hstepA, voffA);
;             PG8_WAIT_V(8); PG8_WAIT_L(0); PG8_BAR; PG8_MMA(0, 0, At, B0); PG8_MMA(0, 1, At, B1); PG8_BAR; PG8_SCHED;
;             PG8_LDA(At, 0, 1); PG8_STAGE(PG8_SB(0, 0), b2, voffB); PG8_STAGE(PG8_SB(0, 1), b2 + hstepB, voffB); PG8_STAGE(PG8_SA(0, 0), a2, voffA);
;             PG8_WAIT_V(8); PG8_WAIT_L(0); PG8_BAR; PG8_MMA(1, 0, At, B0); PG8_MMA(1, 1, At, B1); PG8_BAR; PG8_SCHED;
;             PG8_LDB(B0, 1, 0); PG8_LDB(B1, 1, 1); PG8_SCHED; PG8_LDA(At, 1, 0); PG8_STAGE(PG8_SA(0, 1), a2 + hstepA, voffA);
;             PG8_WAIT_V(8); PG8_WAIT_L(0); PG8_BAR; PG8_MMA(0, 0, At, B0); PG8_MMA(0, 1, At, B1); PG8_BAR; PG8_SCHED;
;             PG8_LDA(At, 1, 1); PG8_STAGE(PG8_SB(1, 0), b3, voffB); PG8_STAGE(PG8_SB(1, 1), b3 + hstepB, voffB); PG8_STAGE(PG8_SA(1, 0), a3, voffA);
;             PG8_WAIT_V(8); PG8_WAIT_L(0); PG8_BAR; PG8_MMA(1, 0, At, B0); PG8_MMA(1, 1, At, B1); PG8_BAR; PG8_SCHED;
	s_add_i32 s89, 0, 0x18000
	v_add_u32_e32 v80, s89, v245
	s_add_i32 s90, 0, 0x1c000
	ds_read_b128 v[130:133], v80
	ds_read_b128 v[134:137], v80 offset:1024
	ds_read_b128 v[138:141], v80 offset:2048
	ds_read_b128 v[142:145], v80 offset:3072
	v_add_u32_e32 v80, s90, v245
	ds_read_b128 v[146:149], v80
	ds_read_b128 v[150:153], v80 offset:1024
	ds_read_b128 v[154:157], v80 offset:2048
	ds_read_b128 v[158:161], v80 offset:3072
	s_add_u32 s22, s58, s0
	s_addc_u32 s23, s59, 0
	s_mov_b32 m0, s70
	ds_read_b128 v[162:165], v248 offset:32768
	ds_read_b128 v[166:169], v248 offset:33792
	ds_read_b128 v[170:173], v248 offset:34816
	ds_read_b128 v[174:177], v248 offset:35840
	ds_read_b128 v[178:181], v248 offset:36864
	ds_read_b128 v[198:201], v248 offset:37888
	ds_read_b128 v[202:205], v248 offset:38912
	ds_read_b128 v[206:209], v248 offset:39936
	global_load_lds_dwordx4 v184, s[58:59]
	s_mov_b32 m0, s71
	s_nop 0
	global_load_lds_dwordx4 v188, s[58:59]
	s_mov_b32 m0, s72
	s_nop 0
	global_load_lds_dwordx4 v184, s[22:23]
	s_mov_b32 m0, s73
	s_nop 0
	global_load_lds_dwordx4 v188, s[22:23]
	s_waitcnt vmcnt(8)
	s_waitcnt lgkmcnt(0)
	v_mfma_f32_16x16x32_bf16 v[4:7], v[130:133], v[162:165], v[4:7]
	v_mfma_f32_16x16x32_bf16 v[0:3], v[138:141], v[162:165], v[0:3]
	s_barrier
	s_waitcnt lgkmcnt(0)
	v_mfma_f32_16x16x32_bf16 v[20:23], v[130:133], v[170:173], v[20:23]
	v_mfma_f32_16x16x32_bf16 v[16:19], v[138:141], v[170:173], v[16:19]
	v_mfma_f32_16x16x32_bf16 v[36:39], v[130:133], v[178:181], v[36:39]
	v_mfma_f32_16x16x32_bf16 v[32:35], v[138:141], v[178:181], v[32:35]
	v_mfma_f32_16x16x32_bf16 v[52:55], v[130:133], v[202:205], v[52:55]
	v_mfma_f32_16x16x32_bf16 v[48:51], v[138:141], v[202:205], v[48:51]
	v_mfma_f32_16x16x32_bf16 v[4:7], v[134:137], v[166:169], v[4:7]
	v_mfma_f32_16x16x32_bf16 v[0:3], v[142:145], v[166:169], v[0:3]
	v_mfma_f32_16x16x32_bf16 v[20:23], v[134:137], v[174:177], v[20:23]
	v_mfma_f32_16x16x32_bf16 v[16:19], v[142:145], v[174:177], v[16:19]
	v_mfma_f32_16x16x32_bf16 v[36:39], v[134:137], v[198:201], v[36:39]
	v_mfma_f32_16x16x32_bf16 v[32:35], v[142:145], v[198:201], v[32:35]
	v_mfma_f32_16x16x32_bf16 v[52:55], v[134:137], v[206:209], v[52:55]
	v_mfma_f32_16x16x32_bf16 v[48:51], v[142:145], v[206:209], v[48:51]
	v_mfma_f32_16x16x32_bf16 v[12:15], v[146:149], v[162:165], v[12:15]
	v_mfma_f32_16x16x32_bf16 v[8:11], v[154:157], v[162:165], v[8:11]
	v_mfma_f32_16x16x32_bf16 v[28:31], v[146:149], v[170:173], v[28:31]
	v_mfma_f32_16x16x32_bf16 v[24:27], v[154:157], v[170:173], v[24:27]
	v_mfma_f32_16x16x32_bf16 v[44:47], v[146:149], v[178:181], v[44:47]
	v_mfma_f32_16x16x32_bf16 v[40:43], v[154:157], v[178:181], v[40:43]
	v_mfma_f32_16x16x32_bf16 v[60:63], v[146:149], v[202:205], v[60:63]
	v_mfma_f32_16x16x32_bf16 v[56:59], v[154:157], v[202:205], v[56:59]
	v_mfma_f32_16x16x32_bf16 v[12:15], v[150:153], v[166:169], v[12:15]
	v_mfma_f32_16x16x32_bf16 v[8:11], v[158:161], v[166:169], v[8:11]
	v_mfma_f32_16x16x32_bf16 v[28:31], v[150:153], v[174:177], v[28:31]
	v_mfma_f32_16x16x32_bf16 v[24:27], v[158:161], v[174:177], v[24:27]
	v_mfma_f32_16x16x32_bf16 v[44:47], v[150:153], v[198:201], v[44:47]
	v_mfma_f32_16x16x32_bf16 v[40:43], v[158:161], v[198:201], v[40:43]
	v_mfma_f32_16x16x32_bf16 v[60:63], v[150:153], v[206:209], v[60:63]
	v_mfma_f32_16x16x32_bf16 v[56:59], v[158:161], v[206:209], v[56:59]
	s_barrier
	s_add_i32 s22, s89, s69
	s_add_u32 vcc_lo, vcc_lo, 0x80
	s_addc_u32 vcc_hi, vcc_hi, 0
	s_mov_b32 m0, s22
	ds_read_b128 v[162:165], v248 offset:49152
	ds_read_b128 v[166:169], v248 offset:50176
	ds_read_b128 v[170:173], v248 offset:51200
	ds_read_b128 v[174:177], v248 offset:52224
	ds_read_b128 v[178:181], v248 offset:53248
	ds_read_b128 v[198:201], v248 offset:54272
	ds_read_b128 v[202:205], v248 offset:55296
	ds_read_b128 v[206:209], v248 offset:56320
	global_load_lds_dwordx4 v186, vcc
	s_add_i32 m0, s22, 0x2000
	s_add_i32 s22, s90, s69
	global_load_lds_dwordx4 v190, vcc
	s_add_u32 vcc_lo, vcc_lo, s33
	s_addc_u32 vcc_hi, vcc_hi, 0
	s_mov_b32 m0, s22
	s_nop 0
	global_load_lds_dwordx4 v186, vcc
	s_add_i32 m0, s22, 0x2000
	s_nop 0
	global_load_lds_dwordx4 v190, vcc
	s_waitcnt vmcnt(6)
	s_waitcnt lgkmcnt(0)
	v_mfma_f32_16x16x32_bf16 v[64:67], v[130:133], v[162:165], v[64:67]
	v_mfma_f32_16x16x32_bf16 v[68:71], v[138:141], v[162:165], v[68:71]
	s_barrier
	s_waitcnt lgkmcnt(0)
	v_mfma_f32_16x16x32_bf16 v[82:85], v[130:133], v[170:173], v[82:85]
	v_mfma_f32_16x16x32_bf16 v[86:89], v[138:141], v[170:173], v[86:89]
	v_mfma_f32_16x16x32_bf16 v[98:101], v[130:133], v[178:181], v[98:101]
	v_mfma_f32_16x16x32_bf16 v[102:105], v[138:141], v[178:181], v[102:105]
	v_mfma_f32_16x16x32_bf16 v[114:117], v[130:133], v[202:205], v[114:117]
	v_mfma_f32_16x16x32_bf16 v[118:121], v[138:141], v[202:205], v[118:121]
	v_mfma_f32_16x16x32_bf16 v[64:67], v[134:137], v[166:169], v[64:67]
	v_mfma_f32_16x16x32_bf16 v[68:71], v[142:145], v[166:169], v[68:71]
	v_mfma_f32_16x16x32_bf16 v[82:85], v[134:137], v[174:177], v[82:85]
	v_mfma_f32_16x16x32_bf16 v[86:89], v[142:145], v[174:177], v[86:89]
	v_mfma_f32_16x16x32_bf16 v[98:101], v[134:137], v[198:201], v[98:101]
	v_mfma_f32_16x16x32_bf16 v[102:105], v[142:145], v[198:201], v[102:105]
	v_mfma_f32_16x16x32_bf16 v[114:117], v[134:137], v[206:209], v[114:117]
	v_mfma_f32_16x16x32_bf16 v[118:121], v[142:145], v[206:209], v[118:121]
	v_mfma_f32_16x16x32_bf16 v[76:79], v[146:149], v[162:165], v[76:79]
	v_mfma_f32_16x16x32_bf16 v[72:75], v[154:157], v[162:165], v[72:75]
	v_mfma_f32_16x16x32_bf16 v[94:97], v[146:149], v[170:173], v[94:97]
	v_mfma_f32_16x16x32_bf16 v[90:93], v[154:157], v[170:173], v[90:93]
	v_mfma_f32_16x16x32_bf16 v[110:113], v[146:149], v[178:181], v[110:113]
	v_mfma_f32_16x16x32_bf16 v[106:109], v[154:157], v[178:181], v[106:109]
	v_mfma_f32_16x16x32_bf16 v[126:129], v[146:149], v[202:205], v[126:129]
	v_mfma_f32_16x16x32_bf16 v[122:125], v[154:157], v[202:205], v[122:125]
	v_mfma_f32_16x16x32_bf16 v[76:79], v[150:153], v[166:169], v[76:79]
	v_mfma_f32_16x16x32_bf16 v[72:75], v[158:161], v[166:169], v[72:75]
	v_mfma_f32_16x16x32_bf16 v[94:97], v[150:153], v[174:177], v[94:97]
	v_mfma_f32_16x16x32_bf16 v[90:93], v[158:161], v[174:177], v[90:93]
	v_mfma_f32_16x16x32_bf16 v[110:113], v[150:153], v[198:201], v[110:113]
	v_mfma_f32_16x16x32_bf16 v[106:109], v[158:161], v[198:201], v[106:109]
	v_mfma_f32_16x16x32_bf16 v[126:129], v[150:153], v[206:209], v[126:129]
	v_mfma_f32_16x16x32_bf16 v[122:125], v[158:161], v[206:209], v[122:125]
	s_barrier
	s_add_u32 s60, s60, 0x100
	s_addc_u32 s61, s61, 0
	s_add_u32 s57, s57, 0x100
	s_addc_u32 s62, s62, 0
	s_cmp_ge_u32 s63, s76
	s_mov_b32 s58, s63
	s_cbranch_scc0 .LBB0_267
	s_branch .Lkloop_exit

; #define PG8_STAGE(bufoff, gbase, voff) do { _Pragma("unroll") for (int _i = 0; _i < 2; ++_i) \
;         __builtin_amdgcn_global_load_lds((const unsigned*)((const char*)(gbase) + (voff)[_i]), (PG8_LAS unsigned*)(lds + (bufoff) + ldsw + _i * 8192), 16, 0, 0); } while (0)
; #define PG8_LDA(dst, b, h) do { _Pragma("unroll") for (int m = 0; m < 4; ++m) _Pragma("unroll") for (int k = 0; k < 2; ++k) dst[m][k] = *(const PG8_LAS bf16x8*)(lds + PG8_SA(b, h) + aoff + m * 2048 + k * 1024); } while (0)
; #define PG8_LDB(dst, b, h) do { _Pragma("unroll") for (int n = 0; n < 2; ++n) _Pragma("unroll") for (int k = 0; k < 2; ++k) dst[n][k] = *(const PG8_LAS bf16x8*)(lds + PG8_SB(b, h) + boff + n * 2048 + k * 1024); } while (0)
; template <class Epi, class Sched, bool ALIGN_EPI = false>
; __device__ __forceinline__ void gemm_phase(PG8_LAS unsigned char* lds, const Gemm g, const Sched& S, const Epi& E, int tid_in) {
;     ...
;         for (int t = 0; t < nt; t += 2) {
;             const bool last = (t == nt - 2);
;             const char* a1 = cA + (size_t)(t + 1) * kstep;
;             const char* a2 = last ? nA : cA + (size_t)(t + 2) * kstep; const char* b2 = last ? nB : cB + (size_t)(t + 2) * kstep;
;             const char* a3 = a2 + kstep; const char* b3 = b2 + kstep;
;             if (last && has_next) S.a_ready(nxt);
;             E.mid(acc, cur, t, tid_, wr, wc);
;             PG8_LDB(B0, 0, 0); PG8_LDB(B1, 0, 1); PG8_SCHED; PG8_LDA(At, 0, 0); PG8_STAGE(PG8_SA(1, 1), a1 + hstepA, voffA);
;             PG8_WAIT_V(8); PG8_WAIT_L(0); PG8_BAR; PG8_MMA(0, 0, At, B0); PG8_MMA(0, 1, At, B1); PG8_BAR; PG8_SCHED;
;             PG8_LDA(At, 0, 1); PG8_STAGE(PG8_SB(0, 0), b2, voffB); PG8_STAGE(PG8_SB(0, 1), b2 + hstepB, voffB); PG8_STAGE(PG8_SA(0, 0), a2, voffA);
;             PG8_WAIT_V(8); PG8_WAIT_L(0); PG8_BAR; PG8_MMA(1, 0, At, B0); PG8_MMA(1, 1, At, B1); PG8_BAR; PG8_SCHED;
;             PG8_LDB(B0, 1, 0); PG8_LDB(B1, 1, 1); PG8_SCHED; PG8_LDA(At, 1, 0); PG8_STAGE(PG8_SA(0, 1), a2 + hstepA, voffA);
;             PG8_WAIT_V(8); PG8_WAIT_L(0); PG8_BAR; PG8_MMA(0, 0, At, B0); PG8_MMA(0, 1, At, B1); PG8_BAR; PG8_SCHED;
;             PG8_LDA(At, 1, 1); PG8_STAGE(PG8_SB(1, 0), b3, voffB); PG8_STAGE(PG8_SB(1, 1), b3 + hstepB, voffB); PG8_STAGE(PG8_SA(1, 0), a3, voffA);
;             PG8_WAIT_V(8); PG8_WAIT_L(0); PG8_BAR; PG8_MMA(1, 0, At, B0); PG8_MMA(1, 1, At, B1); PG8_BAR; PG8_SCHED;
.LBB0_267:
	s_add_i32 s63, s58, 2
	s_add_u32 s22, s60, 0x80
	s_addc_u32 s23, s61, 0
	s_add_i32 s89, 0, 0x10000
	s_cmp_eq_u32 s77, s58
	s_cselect_b32 s59, s19, s23
	s_cselect_b32 s58, s18, s22
	v_add_u32_e32 v80, s89, v245
	s_cselect_b32 s23, s35, s62
	s_cselect_b32 s22, s34, s57
	s_add_i32 s90, 0, 0x14000
	ds_read_b128 v[130:133], v80
	ds_read_b128 v[134:137], v80 offset:1024
	ds_read_b128 v[138:141], v80 offset:2048
	ds_read_b128 v[142:145], v80 offset:3072
	v_add_u32_e32 v80, s90, v245
	ds_read_b128 v[146:149], v80
	ds_read_b128 v[150:153], v80 offset:1024
	ds_read_b128 v[154:157], v80 offset:2048
	ds_read_b128 v[158:161], v80 offset:3072
	s_mov_b32 m0, s74
	ds_read_b128 v[162:165], v248
	ds_read_b128 v[166:169], v248 offset:1024
	ds_read_b128 v[170:173], v248 offset:2048
	ds_read_b128 v[174:177], v248 offset:3072
	ds_read_b128 v[178:181], v248 offset:4096
	ds_read_b128 v[198:201], v248 offset:5120
	ds_read_b128 v[202:205], v248 offset:6144
	ds_read_b128 v[206:209], v248 offset:7168
	global_load_lds_dwordx4 v184, s[60:61]
	s_mov_b32 m0, s75
	s_nop 0
	global_load_lds_dwordx4 v188, s[60:61]
	s_add_i32 m0, s70, 0xc000
	s_nop 0
	global_load_lds_dwordx4 v194, s[60:61]
	s_add_i32 m0, s70, 0xe000
	s_nop 0
	global_load_lds_dwordx4 v196, s[60:61]
	s_waitcnt vmcnt(8)
	s_waitcnt lgkmcnt(0)
	v_mfma_f32_16x16x32_bf16 v[4:7], v[130:133], v[162:165], v[4:7]
	v_mfma_f32_16x16x32_bf16 v[0:3], v[138:141], v[162:165], v[0:3]
	s_barrier
	s_waitcnt lgkmcnt(0)
	v_mfma_f32_16x16x32_bf16 v[20:23], v[130:133], v[170:173], v[20:23]
	v_mfma_f32_16x16x32_bf16 v[16:19], v[138:141], v[170:173], v[16:19]
	v_mfma_f32_16x16x32_bf16 v[36:39], v[130:133], v[178:181], v[36:39]
	v_mfma_f32_16x16x32_bf16 v[32:35], v[138:141], v[178:181], v[32:35]
	v_mfma_f32_16x16x32_bf16 v[52:55], v[130:133], v[202:205], v[52:55]
	v_mfma_f32_16x16x32_bf16 v[48:51], v[138:141], v[202:205], v[48:51]
	v_mfma_f32_16x16x32_bf16 v[4:7], v[134:137], v[166:169], v[4:7]
	v_mfma_f32_16x16x32_bf16 v[0:3], v[142:145], v[166:169], v[0:3]
	v_mfma_f32_16x16x32_bf16 v[20:23], v[134:137], v[174:177], v[20:23]
	v_mfma_f32_16x16x32_bf16 v[16:19], v[142:145], v[174:177], v[16:19]
	v_mfma_f32_16x16x32_bf16 v[36:39], v[134:137], v[198:201], v[36:39]
	v_mfma_f32_16x16x32_bf16 v[32:35], v[142:145], v[198:201], v[32:35]
	v_mfma_f32_16x16x32_bf16 v[52:55], v[134:137], v[206:209], v[52:55]
	v_mfma_f32_16x16x32_bf16 v[48:51], v[142:145], v[206:209], v[48:51]
	v_mfma_f32_16x16x32_bf16 v[12:15], v[146:149], v[162:165], v[12:15]
	v_mfma_f32_16x16x32_bf16 v[8:11], v[154:157], v[162:165], v[8:11]
	v_mfma_f32_16x16x32_bf16 v[28:31], v[146:149], v[170:173], v[28:31]
	v_mfma_f32_16x16x32_bf16 v[24:27], v[154:157], v[170:173], v[24:27]
	v_mfma_f32_16x16x32_bf16 v[44:47], v[146:149], v[178:181], v[44:47]
	v_mfma_f32_16x16x32_bf16 v[40:43], v[154:157], v[178:181], v[40:43]
	v_mfma_f32_16x16x32_bf16 v[60:63], v[146:149], v[202:205], v[60:63]
	v_mfma_f32_16x16x32_bf16 v[56:59], v[154:157], v[202:205], v[56:59]
	v_mfma_f32_16x16x32_bf16 v[12:15], v[150:153], v[166:169], v[12:15]
	v_mfma_f32_16x16x32_bf16 v[8:11], v[158:161], v[166:169], v[8:11]
	v_mfma_f32_16x16x32_bf16 v[28:31], v[150:153], v[174:177], v[28:31]
	v_mfma_f32_16x16x32_bf16 v[24:27], v[158:161], v[174:177], v[24:27]
	v_mfma_f32_16x16x32_bf16 v[44:47], v[150:153], v[198:201], v[44:47]
	v_mfma_f32_16x16x32_bf16 v[40:43], v[158:161], v[198:201], v[40:43]
	v_mfma_f32_16x16x32_bf16 v[60:63], v[150:153], v[206:209], v[60:63]
	v_mfma_f32_16x16x32_bf16 v[56:59], v[158:161], v[206:209], v[56:59]
	s_barrier
	s_add_i32 s89, s89, s69
	s_mov_b64 vcc, s[22:23]
	s_mov_b32 m0, s89
	ds_read_b128 v[162:165], v248 offset:16384
	ds_read_b128 v[166:169], v248 offset:17408
	ds_read_b128 v[170:173], v248 offset:18432
	ds_read_b128 v[174:177], v248 offset:19456
	ds_read_b128 v[178:181], v248 offset:20480
	ds_read_b128 v[198:201], v248 offset:21504
	ds_read_b128 v[202:205], v248 offset:22528
	ds_read_b128 v[206:209], v248 offset:23552
	global_load_lds_dwordx4 v186, s[22:23]
	s_add_i32 m0, s89, 0x2000
	s_add_u32 s22, s22, s33
	s_addc_u32 s23, s23, 0
	s_add_i32 s89, s90, s69
	global_load_lds_dwordx4 v190, vcc
	s_mov_b32 m0, s89
	s_nop 0
	global_load_lds_dwordx4 v186, s[22:23]
	s_add_i32 m0, s89, 0x2000
	s_nop 0
	global_load_lds_dwordx4 v190, s[22:23]
	s_waitcnt vmcnt(6)
	s_waitcnt lgkmcnt(0)
	v_mfma_f32_16x16x32_bf16 v[64:67], v[130:133], v[162:165], v[64:67]
	v_mfma_f32_16x16x32_bf16 v[68:71], v[138:141], v[162:165], v[68:71]
	s_barrier
	s_waitcnt lgkmcnt(0)
	v_mfma_f32_16x16x32_bf16 v[82:85], v[130:133], v[170:173], v[82:85]
	v_mfma_f32_16x16x32_bf16 v[86:89], v[138:141], v[170:173], v[86:89]
	v_mfma_f32_16x16x32_bf16 v[98:101], v[130:133], v[178:181], v[98:101]
	v_mfma_f32_16x16x32_bf16 v[102:105], v[138:141], v[178:181], v[102:105]
	v_mfma_f32_16x16x32_bf16 v[114:117], v[130:133], v[202:205], v[114:117]
	v_mfma_f32_16x16x32_bf16 v[118:121], v[138:141], v[202:205], v[118:121]
	v_mfma_f32_16x16x32_bf16 v[64:67], v[134:137], v[166:169], v[64:67]
	v_mfma_f32_16x16x32_bf16 v[68:71], v[142:145], v[166:169], v[68:71]
	v_mfma_f32_16x16x32_bf16 v[82:85], v[134:137], v[174:177], v[82:85]
	v_mfma_f32_16x16x32_bf16 v[86:89], v[142:145], v[174:177], v[86:89]
	v_mfma_f32_16x16x32_bf16 v[98:101], v[134:137], v[198:201], v[98:101]
	v_mfma_f32_16x16x32_bf16 v[102:105], v[142:145], v[198:201], v[102:105]
	v_mfma_f32_16x16x32_bf16 v[114:117], v[134:137], v[206:209], v[114:117]
	v_mfma_f32_16x16x32_bf16 v[118:121], v[142:145], v[206:209], v[118:121]
	v_mfma_f32_16x16x32_bf16 v[76:79], v[146:149], v[162:165], v[76:79]
	v_mfma_f32_16x16x32_bf16 v[72:75], v[154:157], v[162:165], v[72:75]
	v_mfma_f32_16x16x32_bf16 v[94:97], v[146:149], v[170:173], v[94:97]
	v_mfma_f32_16x16x32_bf16 v[90:93], v[154:157], v[170:173], v[90:93]
	v_mfma_f32_16x16x32_bf16 v[110:113], v[146:149], v[178:181], v[110:113]
	v_mfma_f32_16x16x32_bf16 v[106:109], v[154:157], v[178:181], v[106:109]
	v_mfma_f32_16x16x32_bf16 v[126:129], v[146:149], v[202:205], v[126:129]
	v_mfma_f32_16x16x32_bf16 v[122:125], v[154:157], v[202:205], v[122:125]
	v_mfma_f32_16x16x32_bf16 v[76:79], v[150:153], v[166:169], v[76:79]
	v_mfma_f32_16x16x32_bf16 v[72:75], v[158:161], v[166:169], v[72:75]
	v_mfma_f32_16x16x32_bf16 v[94:97], v[150:153], v[174:177], v[94:97]
	v_mfma_f32_16x16x32_bf16 v[90:93], v[158:161], v[174:177], v[90:93]
	v_mfma_f32_16x16x32_bf16 v[110:113], v[150:153], v[198:201], v[110:113]
	v_mfma_f32_16x16x32_bf16 v[106:109], v[158:161], v[198:201], v[106:109]
	v_mfma_f32_16x16x32_bf16 v[126:129], v[150:153], v[206:209], v[126:129]
	v_mfma_f32_16x16x32_bf16 v[122:125], v[158:161], v[206:209], v[122:125]
	s_barrier
; #define PG8_STAGE(bufoff, gbase, voff) do { _Pragma("unroll") for (int _i = 0; _i < 2; ++_i) \
;         __builtin_amdgcn_global_load_lds((const unsigned*)((const char*)(gbase) + (voff)[_i]), (PG8_LAS unsigned*)(lds + (bufoff) + ldsw + _i * 8192), 16, 0, 0); } while (0)
; #define PG8_WAIT_V(n) asm volatile("s_waitcnt vmcnt(" #n ")" ::: "memory")
; template <class Epi, class Sched, bool ALIGN_EPI = false>
; __device__ __forceinline__ void gemm_phase(PG8_LAS unsigned char* lds, const Gemm g, const Sched& S, const Epi& E, int tid_in) {
;     ...
;         for (int t = 0; t < nt; t += 2) {
;             const bool last = (t == nt - 2);
;             const char* a1 = cA + (size_t)(t + 1) * kstep;
;             const char* a2 = last ? nA : cA + (size_t)(t + 2) * kstep; const char* b2 = last ? nB : cB + (size_t)(t + 2) * kstep;
;             const char* a3 = a2 + kstep; const char* b3 = b2 + kstep;
;             if (last && has_next) S.a_ready(nxt);
;             E.mid(acc, cur, t, tid_, wr, wc);
;             PG8_LDB(B0, 0, 0); PG8_LDB(B1, 0, 1); PG8_SCHED; PG8_LDA(At, 0, 0); PG8_STAGE(PG8_SA(1, 1), a1 + hstepA, voffA);
;             PG8_WAIT_V(8); PG8_WAIT_L(0); PG8_BAR; PG8_MMA(0, 0, At, B0); PG8_MMA(0, 1, At, B1); PG8_BAR; PG8_SCHED;
;             PG8_LDA(At, 0, 1); PG8_STAGE(PG8_SB(0, 0), b2, voffB); PG8_STAGE(PG8_SB(0, 1), b2 + hstepB, voffB); PG8_STAGE(PG8_SA(0, 0), a2, voffA);
;             PG8_WAIT_V(8); PG8_WAIT_L(0); PG8_BAR; PG8_MMA(1, 0, At, B0); PG8_MMA(1, 1, At, B1); PG8_BAR; PG8_SCHED;
;             PG8_LDB(B0, 1, 0); PG8_LDB(B1, 1, 1); PG8_SCHED; PG8_LDA(At, 1, 0); PG8_STAGE(PG8_SA(0, 1), a2 + hstepA, voffA);
;             PG8_WAIT_V(8); PG8_WAIT_L(0); PG8_BAR; PG8_MMA(0, 0, At, B0); PG8_MMA(0, 1, At, B1); PG8_BAR; PG8_SCHED;
;             PG8_LDA(At, 1, 1); PG8_STAGE(PG8_SB(1, 0), b3, voffB); PG8_STAGE(PG8_SB(1, 1), b3 + hstepB, voffB); PG8_STAGE(PG8_SA(1, 0), a3, voffA);
;             PG8_WAIT_V(8); PG8_WAIT_L(0); PG8_BAR; PG8_MMA(1, 0, At, B0); PG8_MMA(1, 1, At, B1); PG8_BAR; PG8_SCHED;
;         }
;         if constexpr (ALIGN_EPI) { if (wr == 0) PG8_BAR; }
;         E(acc, cur, wr, wc, fr, fq); S.done(cur);
;         if (!has_next) break;
;         E.init(acc, nxt, wr, wc, fr, fq);
;         cur = nxt; cA = nA; cB = nB; ++ui;
;         if constexpr (ALIGN_EPI) { if (wr == 1) PG8_BAR; }
;     }
;     PG8_WAIT_V(0);
	s_add_i32 s89, 0, 0x18000
	v_add_u32_e32 v80, s89, v245
	s_add_i32 s90, 0, 0x1c000
	ds_read_b128 v[130:133], v80
	ds_read_b128 v[134:137], v80 offset:1024
	ds_read_b128 v[138:141], v80 offset:2048
	ds_read_b128 v[142:145], v80 offset:3072
	v_add_u32_e32 v80, s90, v245
	ds_read_b128 v[146:149], v80
	ds_read_b128 v[150:153], v80 offset:1024
	ds_read_b128 v[154:157], v80 offset:2048
	ds_read_b128 v[158:161], v80 offset:3072
	s_add_u32 s22, s58, s0
	s_addc_u32 s23, s59, 0
	s_mov_b32 m0, s70
	ds_read_b128 v[162:165], v248 offset:32768
	ds_read_b128 v[166:169], v248 offset:33792
	ds_read_b128 v[170:173], v248 offset:34816
	ds_read_b128 v[174:177], v248 offset:35840
	ds_read_b128 v[178:181], v248 offset:36864
	ds_read_b128 v[198:201], v248 offset:37888
	ds_read_b128 v[202:205], v248 offset:38912
	ds_read_b128 v[206:209], v248 offset:39936
	global_load_lds_dwordx4 v184, s[58:59]
	s_mov_b32 m0, s71
	s_nop 0
	global_load_lds_dwordx4 v188, s[58:59]
	s_mov_b32 m0, s72
	s_nop 0
	global_load_lds_dwordx4 v184, s[22:23]
	s_mov_b32 m0, s73
	s_nop 0
	global_load_lds_dwordx4 v188, s[22:23]
	s_waitcnt vmcnt(8)
	s_waitcnt lgkmcnt(0)
	v_mfma_f32_16x16x32_bf16 v[4:7], v[130:133], v[162:165], v[4:7]
	v_mfma_f32_16x16x32_bf16 v[0:3], v[138:141], v[162:165], v[0:3]
	s_barrier
	s_waitcnt lgkmcnt(0)
	v_mfma_f32_16x16x32_bf16 v[20:23], v[130:133], v[170:173], v[20:23]
	v_mfma_f32_16x16x32_bf16 v[16:19], v[138:141], v[170:173], v[16:19]
	v_mfma_f32_16x16x32_bf16 v[36:39], v[130:133], v[178:181], v[36:39]
	v_mfma_f32_16x16x32_bf16 v[32:35], v[138:141], v[178:181], v[32:35]
	v_mfma_f32_16x16x32_bf16 v[52:55], v[130:133], v[202:205], v[52:55]
	v_mfma_f32_16x16x32_bf16 v[48:51], v[138:141], v[202:205], v[48:51]
	v_mfma_f32_16x16x32_bf16 v[4:7], v[134:137], v[166:169], v[4:7]
	v_mfma_f32_16x16x32_bf16 v[0:3], v[142:145], v[166:169], v[0:3]
	v_mfma_f32_16x16x32_bf16 v[20:23], v[134:137], v[174:177], v[20:23]
	v_mfma_f32_16x16x32_bf16 v[16:19], v[142:145], v[174:177], v[16:19]
	v_mfma_f32_16x16x32_bf16 v[36:39], v[134:137], v[198:201], v[36:39]
	v_mfma_f32_16x16x32_bf16 v[32:35], v[142:145], v[198:201], v[32:35]
	v_mfma_f32_16x16x32_bf16 v[52:55], v[134:137], v[206:209], v[52:55]
	v_mfma_f32_16x16x32_bf16 v[48:51], v[142:145], v[206:209], v[48:51]
	v_mfma_f32_16x16x32_bf16 v[12:15], v[146:149], v[162:165], v[12:15]
	v_mfma_f32_16x16x32_bf16 v[8:11], v[154:157], v[162:165], v[8:11]
	v_mfma_f32_16x16x32_bf16 v[28:31], v[146:149], v[170:173], v[28:31]
	v_mfma_f32_16x16x32_bf16 v[24:27], v[154:157], v[170:173], v[24:27]
	v_mfma_f32_16x16x32_bf16 v[44:47], v[146:149], v[178:181], v[44:47]
	v_mfma_f32_16x16x32_bf16 v[40:43], v[154:157], v[178:181], v[40:43]
	v_mfma_f32_16x16x32_bf16 v[60:63], v[146:149], v[202:205], v[60:63]
	v_mfma_f32_16x16x32_bf16 v[56:59], v[154:157], v[202:205], v[56:59]
	v_mfma_f32_16x16x32_bf16 v[12:15], v[150:153], v[166:169], v[12:15]
	v_mfma_f32_16x16x32_bf16 v[8:11], v[158:161], v[166:169], v[8:11]
	v_mfma_f32_16x16x32_bf16 v[28:31], v[150:153], v[174:177], v[28:31]
	v_mfma_f32_16x16x32_bf16 v[24:27], v[158:161], v[174:177], v[24:27]
	v_mfma_f32_16x16x32_bf16 v[44:47], v[150:153], v[198:201], v[44:47]
	v_mfma_f32_16x16x32_bf16 v[40:43], v[158:161], v[198:201], v[40:43]
	v_mfma_f32_16x16x32_bf16 v[60:63], v[150:153], v[206:209], v[60:63]
	v_mfma_f32_16x16x32_bf16 v[56:59], v[158:161], v[206:209], v[56:59]
	s_barrier
	s_add_i32 s22, s89, s69
	s_add_u32 vcc_lo, vcc_lo, 0x80
	s_addc_u32 vcc_hi, vcc_hi, 0
	s_mov_b32 m0, s22
	ds_read_b128 v[162:165], v248 offset:49152
	ds_read_b128 v[166:169], v248 offset:50176
	ds_read_b128 v[170:173], v248 offset:51200
	ds_read_b128 v[174:177], v248 offset:52224
	ds_read_b128 v[178:181], v248 offset:53248
	ds_read_b128 v[198:201], v248 offset:54272
	ds_read_b128 v[202:205], v248 offset:55296
	ds_read_b128 v[206:209], v248 offset:56320
	global_load_lds_dwordx4 v186, vcc
	s_add_i32 m0, s22, 0x2000
	s_add_i32 s22, s90, s69
	global_load_lds_dwordx4 v190, vcc
	s_add_u32 vcc_lo, vcc_lo, s33
	s_addc_u32 vcc_hi, vcc_hi, 0
	s_mov_b32 m0, s22
	s_nop 0
	global_load_lds_dwordx4 v186, vcc
	s_add_i32 m0, s22, 0x2000
	s_nop 0
	global_load_lds_dwordx4 v190, vcc
	s_waitcnt vmcnt(6)
	s_waitcnt lgkmcnt(0)
	v_mfma_f32_16x16x32_bf16 v[64:67], v[130:133], v[162:165], v[64:67]
	v_mfma_f32_16x16x32_bf16 v[68:71], v[138:141], v[162:165], v[68:71]
	s_barrier
	s_waitcnt lgkmcnt(0)
	v_mfma_f32_16x16x32_bf16 v[82:85], v[130:133], v[170:173], v[82:85]
	v_mfma_f32_16x16x32_bf16 v[86:89], v[138:141], v[170:173], v[86:89]
	v_mfma_f32_16x16x32_bf16 v[98:101], v[130:133], v[178:181], v[98:101]
	v_mfma_f32_16x16x32_bf16 v[102:105], v[138:141], v[178:181], v[102:105]
	v_mfma_f32_16x16x32_bf16 v[114:117], v[130:133], v[202:205], v[114:117]
	v_mfma_f32_16x16x32_bf16 v[118:121], v[138:141], v[202:205], v[118:121]
	v_mfma_f32_16x16x32_bf16 v[64:67], v[134:137], v[166:169], v[64:67]
	v_mfma_f32_16x16x32_bf16 v[68:71], v[142:145], v[166:169], v[68:71]
	v_mfma_f32_16x16x32_bf16 v[82:85], v[134:137], v[174:177], v[82:85]
	v_mfma_f32_16x16x32_bf16 v[86:89], v[142:145], v[174:177], v[86:89]
	v_mfma_f32_16x16x32_bf16 v[98:101], v[134:137], v[198:201], v[98:101]
	v_mfma_f32_16x16x32_bf16 v[102:105], v[142:145], v[198:201], v[102:105]
	v_mfma_f32_16x16x32_bf16 v[114:117], v[134:137], v[206:209], v[114:117]
	v_mfma_f32_16x16x32_bf16 v[118:121], v[142:145], v[206:209], v[118:121]
	v_mfma_f32_16x16x32_bf16 v[76:79], v[146:149], v[162:165], v[76:79]
	v_mfma_f32_16x16x32_bf16 v[72:75], v[154:157], v[162:165], v[72:75]
	v_mfma_f32_16x16x32_bf16 v[94:97], v[146:149], v[170:173], v[94:97]
	v_mfma_f32_16x16x32_bf16 v[90:93], v[154:157], v[170:173], v[90:93]
	v_mfma_f32_16x16x32_bf16 v[110:113], v[146:149], v[178:181], v[110:113]
	v_mfma_f32_16x16x32_bf16 v[106:109], v[154:157], v[178:181], v[106:109]
	v_mfma_f32_16x16x32_bf16 v[126:129], v[146:149], v[202:205], v[126:129]
	v_mfma_f32_16x16x32_bf16 v[122:125], v[154:157], v[202:205], v[122:125]
	v_mfma_f32_16x16x32_bf16 v[76:79], v[150:153], v[166:169], v[76:79]
	v_mfma_f32_16x16x32_bf16 v[72:75], v[158:161], v[166:169], v[72:75]
	v_mfma_f32_16x16x32_bf16 v[94:97], v[150:153], v[174:177], v[94:97]
	v_mfma_f32_16x16x32_bf16 v[90:93], v[158:161], v[174:177], v[90:93]
	v_mfma_f32_16x16x32_bf16 v[110:113], v[150:153], v[198:201], v[110:113]
	v_mfma_f32_16x16x32_bf16 v[106:109], v[158:161], v[198:201], v[106:109]
	v_mfma_f32_16x16x32_bf16 v[126:129], v[150:153], v[206:209], v[126:129]
	v_mfma_f32_16x16x32_bf16 v[122:125], v[158:161], v[206:209], v[122:125]
	s_barrier
	s_add_u32 s60, s60, 0x100
	s_addc_u32 s61, s61, 0
	s_add_u32 s57, s57, 0x100
	s_addc_u32 s62, s62, 0
	s_cmp_ge_u32 s63, s76
	s_mov_b32 s58, s63
	s_cbranch_scc0 .LBB0_267
.Lkloop_exit:
	s_setprio 0
	s_and_b64 vcc, exec, s[14:15]
	s_cbranch_vccnz .LBB0_271
	s_cmp_lt_i32 s64, 3
	s_mov_b64 s[58:59], -1
	s_cbranch_scc0 .LBB0_272
